# v81 + attention LDS staging writes with immediate buffer offsets / per-unit base registers (5 address VALU per tile removed) and the x+0 add dropped
# speedup vs baseline: 1.0172x; 1.0005x over previous
; DI void attn_unit(LAS unsigned char* lds, int wid, int b, int h, int qb) {
;     ...
;             float ls = 0.f;
; #pragma unroll
;             for (int i = 0; i < 16; ++i) { s0[i] = __builtin_amdgcn_exp2f(s0[i] - mnew); s1[i] = __builtin_amdgcn_exp2f(s1[i] - mnew); ls += s0[i] + s1[i]; }
.LBB0_1076:
	v_exp_f32_e32 v80, v80
	v_exp_f32_e32 v96, v96
	v_exp_f32_e32 v81, v81
	v_exp_f32_e32 v97, v97
	v_exp_f32_e32 v82, v82
	v_exp_f32_e32 v98, v98
	v_exp_f32_e32 v83, v83
	v_exp_f32_e32 v99, v99
	v_add_f32_e32 v119, v96, v80
	v_exp_f32_e32 v84, v84
	v_exp_f32_e32 v100, v100

; DI unsigned pk2(float a, float b) { f32x2 f = {a, b}; bf16v2 r = __builtin_convertvector(f, bf16v2); return __builtin_bit_cast(unsigned, r); }
; #define VLD(dst, j, dt) do { LAS unsigned char* va_ = vb + (32 * (dt) + n) * VROW + (16 * (j) + 4 * g) * 2; const u32x2 lo_ = *(const LAS u32x2*)(va_), hi_ = *(const LAS u32x2*)(va_ + 16); dst = (u32x4){lo_.x, lo_.y, hi_.x, hi_.y}; } while (0)
; DI void attn_unit(LAS unsigned char* lds, int wid, int b, int h, int qb) {
;     ...
;             for (int i = 0; i < 16; ++i) { s0[i] = __builtin_amdgcn_exp2f(s0[i] - mnew); s1[i] = __builtin_amdgcn_exp2f(s1[i] - mnew); ls += s0[i] + s1[i]; }
;             lrow = lrow * alpha + ls;
;             if (__builtin_amdgcn_ballot_w64(alpha != 1.f) != 0ull) {
; #pragma unroll
;                 for (int dt = 0; dt < 4; ++dt)
; #pragma unroll
;                     for (int i = 0; i < 16; ++i) o[dt][i] *= alpha;
;             }
;             bf16x8 pf[4];
; #pragma unroll
;             for (int jj = 0; jj < 2; ++jj) { u32x4 w0, w1;
;                 w0.x = pk2(s0[8 * jj + 0], s0[8 * jj + 1]); w0.y = pk2(s0[8 * jj + 2], s0[8 * jj + 3]); w0.z = pk2(s0[8 * jj + 4], s0[8 * jj + 5]); w0.w = pk2(s0[8 * jj + 6], s0[8 * jj + 7]);
;                 w1.x = pk2(s1[8 * jj + 0], s1[8 * jj + 1]); w1.y = pk2(s1[8 * jj + 2], s1[8 * jj + 3]); w1.z = pk2(s1[8 * jj + 4], s1[8 * jj + 5]); w1.w = pk2(s1[8 * jj + 6], s1[8 * jj + 7]);
;                 pf[jj] = __builtin_bit_cast(bf16x8, w0); pf[2 + jj] = __builtin_bit_cast(bf16x8, w1); }
; #pragma unroll
;             for (int j = 0; j < 4; ++j) {
;                 if (j < 3) {
; #pragma unroll
;                     for (int dt = 0; dt < 4; ++dt) VLD(vf[(j + 1) & 1][dt], j + 1, dt);
;                 }
; #pragma unroll
;                 for (int dt = 0; dt < 4; ++dt) o[dt] = __builtin_amdgcn_mfma_f32_32x32x16_bf16(__builtin_bit_cast(bf16x8, vf[j & 1][dt]), pf[j], o[dt], 0, 0, 0);
;                 __builtin_amdgcn_sched_barrier(0); }
	v_add_f32_e32 v120, v97, v81
	v_exp_f32_e32 v85, v85
	v_exp_f32_e32 v101, v101
	v_add_f32_e32 v119, v120, v119
	v_add_f32_e32 v120, v98, v82
	v_exp_f32_e32 v86, v86
	v_exp_f32_e32 v102, v102
	v_add_f32_e32 v119, v120, v119
	v_add_f32_e32 v120, v99, v83
	v_exp_f32_e32 v87, v87
	v_exp_f32_e32 v103, v103
	v_add_f32_e32 v119, v120, v119
	v_add_f32_e32 v120, v100, v84
	v_exp_f32_e32 v88, v88
	v_exp_f32_e32 v104, v104
	v_add_f32_e32 v119, v120, v119
	v_add_f32_e32 v120, v101, v85
	v_exp_f32_e32 v89, v89
	v_exp_f32_e32 v105, v105
	v_add_f32_e32 v119, v120, v119
	v_add_f32_e32 v120, v102, v86
	v_exp_f32_e32 v90, v90
	v_exp_f32_e32 v106, v106
	v_add_f32_e32 v119, v120, v119
	v_add_f32_e32 v120, v103, v87
	v_exp_f32_e32 v91, v91
	v_exp_f32_e32 v107, v107
	v_add_f32_e32 v119, v120, v119
	v_add_f32_e32 v120, v104, v88
	v_exp_f32_e32 v92, v92
	v_exp_f32_e32 v108, v108
	v_add_f32_e32 v119, v120, v119
	v_add_f32_e32 v120, v105, v89
	v_exp_f32_e32 v93, v93
	v_exp_f32_e32 v109, v109
	v_add_f32_e32 v119, v120, v119
	v_add_f32_e32 v120, v106, v90
	v_exp_f32_e32 v94, v94
	v_exp_f32_e32 v110, v110
	v_add_f32_e32 v119, v120, v119
	v_add_f32_e32 v120, v107, v91
	v_exp_f32_e32 v95, v95
	v_exp_f32_e32 v111, v111
	v_add_f32_e32 v119, v120, v119
	v_add_f32_e32 v120, v108, v92
	v_add_f32_e32 v119, v120, v119
	v_add_f32_e32 v120, v109, v93
	v_cvt_pk_bf16_f32 v80, v80, v81
	v_cvt_pk_bf16_f32 v81, v82, v83
	v_cvt_pk_bf16_f32 v82, v84, v85
	v_cvt_pk_bf16_f32 v83, v86, v87
	v_add_f32_e32 v119, v120, v119
	v_cvt_pk_bf16_f32 v86, v92, v93
	v_mfma_f32_32x32x16_bf16 v[64:79], v[2:5], v[80:83], v[64:79]
	v_add_f32_e32 v2, v110, v94
	v_add_f32_e32 v2, v2, v119
	v_add_f32_e32 v3, v111, v95
	v_add_f32_e32 v118, v3, v2
	v_cvt_pk_bf16_f32 v2, v96, v97
	v_cvt_pk_bf16_f32 v3, v98, v99
	v_cvt_pk_bf16_f32 v4, v100, v101
	s_waitcnt lgkmcnt(1)
	v_mfma_f32_32x32x16_bf16 v[48:63], v[112:115], v[80:83], v[48:63]
	v_cvt_pk_bf16_f32 v5, v102, v103
	v_cvt_pk_bf16_f32 v87, v94, v95
	v_fmac_f32_e32 v118, v185, v0
	v_cvt_pk_bf16_f32 v84, v88, v89
	v_cvt_pk_bf16_f32 v85, v90, v91
	v_cvt_pk_bf16_f32 v88, v104, v105
	v_cvt_pk_bf16_f32 v89, v106, v107
	v_mfma_f32_32x32x16_bf16 v[32:47], v[10:13], v[80:83], v[32:47]
	ds_read2_b64 v[10:13], v15 offset0:132 offset1:134
	ds_read2_b64 v[92:95], v116 offset0:164 offset1:166
	ds_read2_b64 v[96:99], v117 offset0:196 offset1:198
	ds_read2_b64 v[100:103], v14 offset0:228 offset1:230
	v_cvt_pk_bf16_f32 v90, v108, v109
	v_cvt_pk_bf16_f32 v91, v110, v111
	s_waitcnt lgkmcnt(4)
	v_mfma_f32_32x32x16_bf16 v[16:31], v[6:9], v[80:83], v[16:31]
	s_waitcnt lgkmcnt(3)
	v_mfma_f32_32x32x16_bf16 v[64:79], v[10:13], v[84:87], v[64:79]
	s_waitcnt lgkmcnt(2)
	v_mfma_f32_32x32x16_bf16 v[48:63], v[92:95], v[84:87], v[48:63]
	ds_read2_b64 v[6:9], v15 offset0:136 offset1:138
	ds_read2_b64 v[10:13], v116 offset0:168 offset1:170
	ds_read2_b64 v[80:83], v117 offset0:200 offset1:202
	ds_read2_b64 v[92:95], v14 offset0:232 offset1:234
	s_waitcnt lgkmcnt(5)
	v_mfma_f32_32x32x16_bf16 v[32:47], v[96:99], v[84:87], v[32:47]
	s_waitcnt lgkmcnt(4)
	v_mfma_f32_32x32x16_bf16 v[16:31], v[100:103], v[84:87], v[16:31]
	s_waitcnt lgkmcnt(3)
	v_mfma_f32_32x32x16_bf16 v[64:79], v[6:9], v[2:5], v[64:79]
	s_waitcnt lgkmcnt(2)
	v_mfma_f32_32x32x16_bf16 v[48:63], v[10:13], v[2:5], v[48:63]
	s_waitcnt lgkmcnt(1)
	v_mfma_f32_32x32x16_bf16 v[32:47], v[80:83], v[2:5], v[32:47]
	ds_read2_b64 v[6:9], v15 offset0:140 offset1:142
	ds_read2_b64 v[10:13], v116 offset0:172 offset1:174
	ds_read2_b64 v[80:83], v117 offset0:204 offset1:206
	ds_read2_b64 v[84:87], v14 offset0:236 offset1:238
	s_waitcnt lgkmcnt(4)
	v_mfma_f32_32x32x16_bf16 v[16:31], v[92:95], v[2:5], v[16:31]
	s_waitcnt lgkmcnt(3)
	v_mfma_f32_32x32x16_bf16 v[64:79], v[6:9], v[88:91], v[64:79]
	s_waitcnt lgkmcnt(2)
	v_mfma_f32_32x32x16_bf16 v[48:63], v[10:13], v[88:91], v[48:63]
	s_waitcnt lgkmcnt(1)
	v_mfma_f32_32x32x16_bf16 v[32:47], v[80:83], v[88:91], v[32:47]
	s_waitcnt lgkmcnt(0)
	v_mfma_f32_32x32x16_bf16 v[16:31], v[84:87], v[88:91], v[16:31]
	v_mov_b32_e32 v185, v118

; DI int lane_id() { int l = __builtin_amdgcn_mbcnt_hi(-1, __builtin_amdgcn_mbcnt_lo(-1, 0)); asm volatile("" : "+v"(l)); return l; }
; #define A_LOAD(kt) do { const size_t ko = (size_t)(kt) * 64; st0 = *(const u32x4*)(kn_src + ko * 2048); st1 = *(const u32x4*)(kn_src + (ko + 32) * 2048); \
;         st2 = *(const u32x4*)(kr_src + ko * 64); st3 = *(const u32x4*)(v_src + ko); st4 = *(const u32x4*)(v_src + ko + (size_t)64 * 8192); } while (0)
; DI void attn_unit(LAS unsigned char* lds, int wid, int b, int h, int qb) {
;     ...
;     const int lane = lane_id(), tid = wid * 64 + lane, n = lane & 31, g = lane >> 5;
;     const int q0 = qb * 256 + wid * 32, cq = q0 >> 6, nkt = 4 * qb + 4;
;     const size_t tokq = (size_t)b * SEQ + q0 + n;
;     const bf16_t* Q = WSB(OFF_Q); const bf16_t* KN = WSB(OFF_KN); const bf16_t* KR = WSB(OFF_KR); const bf16_t* VT = WSB(OFF_VT2);
;     bf16x8 qf[12];
; #pragma unroll
;     for (int ks = 0; ks < 12; ++ks) qf[ks] = *(const bf16x8*)(Q + tokq * 3072 + h * 192 + ks * 16 + g * 8);
;     f32x16 o[4];
; #pragma unroll
;     for (int dt = 0; dt < 4; ++dt)
; #pragma unroll
;         for (int i = 0; i < 16; ++i) o[dt][i] = 0.f;
;     float mrow = -__builtin_inff(), lrow = 0.f;
;     const int krow = tid >> 4, kc16 = tid & 15, rrow = tid >> 3, rc8 = tid & 7;
;     const bf16_t* kn_src = KN + ((size_t)b * SEQ + krow) * 2048 + h * 128 + kc16 * 8;
;     const bf16_t* kr_src = KR + ((size_t)b * SEQ + rrow) * 64 + rc8 * 8;
;     const bf16_t* v_src = VT + ((size_t)h * 128 + rrow) * 8192 + (size_t)b * SEQ + rc8 * 8;
;     const int kn_dst = krow * KROW + kc16 * 16, kr_dst = rrow * KROW + 256 + rc8 * 16, v_dst = KBYTES + rrow * VROW + rc8 * 16;
;     u32x4 st0, st1, st2, st3, st4;
;     ...
;     A_LOAD(0); A_WRITE(0); __syncthreads();
; DI void phase_attn(CP& p, LAS unsigned char* lds, int wid) {
;     ...
;         const int xcd = P & 7, idx = P >> 3, bh = xcd * 4 + (idx >> 3), x = idx & 7, b = bh >> 4, h = bh & 15;
;         attn_unit(lds, wid, b, h, 15 - x);
.LBB0_1078:
	s_lshl_b32 s4, s55, 2
	s_and_b32 s4, s4, 28
	s_ashr_i32 s59, s55, 6
	s_mov_b64 s[16:17], s[0:1]
	v_mov_b32_e32 v183, v201
	s_add_i32 s4, s4, s59
	s_bfe_u32 s56, s55, 0x30003
	s_load_dwordx2 s[24:25], s[16:17], 0xa8
	s_ashr_i32 s22, s4, 4
	s_and_b32 s20, s4, 15
	s_xor_b32 s4, s56, 15
	s_lshl_b32 s18, s4, 8
	s_ashr_i32 s23, s22, 31
	s_lshr_b32 s57, s55, 3
	s_add_i32 s21, s18, s29
	s_lshl_b32 s61, s4, 2
	s_lshl_b64 s[16:17], s[22:23], 12
	v_and_b32_e32 v197, 31, v183
	s_add_u32 s26, s16, s21
	v_or_b32_e32 v0, s26, v197
	s_waitcnt lgkmcnt(0)
	v_mov_b64_e32 v[2:3], s[24:25]
	v_mad_u64_u32 v[2:3], s[18:19], v0, s37, v[2:3]
	v_add_u32_e32 v0, s28, v183
	v_ashrrev_i32_e32 v26, 3, v0
	v_ashrrev_i32_e32 v27, 31, v26
	s_addc_u32 s27, s17, 0
	s_mul_i32 s58, s20, 0xc0
	v_ashrrev_i32_e32 v24, 4, v0
	v_lshl_add_u64 v[4:5], s[16:17], 0, v[26:27]
	v_mad_i32_i24 v3, s27, v200, v3
	s_lshl_b32 s4, s58, 1
	v_ashrrev_i32_e32 v25, 31, v24
	v_lshlrev_b64 v[4:5], 7, v[4:5]
	v_lshlrev_b32_e32 v6, 4, v183
	v_lshl_add_u64 v[22:23], v[2:3], 0, s[4:5]
	v_lshl_add_u64 v[2:3], s[16:17], 0, v[24:25]
	s_lshl_b32 s4, s20, 7
	v_lshl_add_u64 v[4:5], s[24:25], 0, v[4:5]
	v_and_b32_e32 v28, 0x70, v6
	v_mov_b32_e32 v29, v1
	v_lshlrev_b64 v[2:3], 12, v[2:3]
	v_lshl_add_u64 v[10:11], v[4:5], 0, v[28:29]
	v_lshl_add_u64 v[4:5], v[26:27], 0, s[4:5]
	v_and_b32_e32 v32, 15, v183
	v_lshl_add_u64 v[2:3], s[24:25], 0, v[2:3]
	s_lshl_b32 s18, s20, 8
	s_mov_b32 s19, s5
	v_lshlrev_b64 v[4:5], 14, v[4:5]
	v_lshl_add_u64 v[2:3], v[2:3], 0, s[18:19]
	v_lshlrev_b32_e32 v0, 4, v32
	v_lshl_add_u64 v[4:5], s[24:25], 0, v[4:5]
	s_lshl_b64 s[18:19], s[22:23], 13
	v_lshl_add_u64 v[2:3], v[2:3], 0, v[0:1]
	v_lshl_add_u64 v[4:5], v[4:5], 0, s[18:19]
	v_lshl_add_u64 v[18:19], v[4:5], 0, v[28:29]
	v_add_co_u32_e32 v4, vcc, s40, v2
	v_ashrrev_i32_e32 v29, 5, v183
	s_nop 0
	v_addc_co_u32_e32 v5, vcc, 0, v3, vcc
	v_add_co_u32_e32 v6, vcc, s41, v2
	v_lshlrev_b32_e32 v184, 3, v29
	s_nop 0
	v_addc_co_u32_e32 v7, vcc, 0, v3, vcc
	v_add_co_u32_e32 v10, vcc, s42, v10
	v_ashrrev_i32_e32 v185, 31, v184
	s_nop 0
	v_addc_co_u32_e32 v11, vcc, 0, v11, vcc
	v_add_co_u32_e32 v14, vcc, s43, v18
	v_lshl_add_u64 v[22:23], v[184:185], 1, v[22:23]
	s_nop 0
	v_addc_co_u32_e32 v15, vcc, 0, v19, vcc
	v_add_co_u32_e32 v18, vcc, s44, v18
	global_load_dwordx4 v[2:5], v[4:5], off
	s_nop 0
	global_load_dwordx4 v[6:9], v[6:7], off
	v_addc_co_u32_e32 v19, vcc, 0, v19, vcc
	v_lshl_add_u64 v[30:31], v[22:23], 0, s[8:9]
	v_add_co_u32_e32 v22, vcc, s38, v22
	global_load_dwordx4 v[10:13], v[10:11], off
	s_nop 0
	v_addc_co_u32_e32 v23, vcc, 0, v23, vcc
	global_load_dwordx4 v[14:17], v[14:15], off
	s_lshr_b32 s62, s21, 6
	global_load_dwordx4 v[18:21], v[18:19], off
	s_nop 0
	global_load_dwordx4 v[138:141], v[30:31], off offset:32
	global_load_dwordx4 v[134:137], v[30:31], off offset:64
	global_load_dwordx4 v[130:133], v[30:31], off offset:96
	global_load_dwordx4 v[126:129], v[30:31], off offset:128
	global_load_dwordx4 v[122:125], v[30:31], off offset:160
	global_load_dwordx4 v[118:121], v[30:31], off offset:192
	global_load_dwordx4 v[114:117], v[30:31], off offset:224
	global_load_dwordx4 v[110:113], v[30:31], off offset:256
	global_load_dwordx4 v[106:109], v[30:31], off offset:288
	global_load_dwordx4 v[102:105], v[30:31], off offset:320
	global_load_dwordx4 v[142:145], v[22:23], off
	global_load_dwordx4 v[98:101], v[30:31], off offset:352
	v_mad_u64_u32 v[186:187], s[20:21], v24, s39, v[0:1]
	v_mad_u64_u32 v[188:189], s[20:21], v26, s39, v[28:29]
	v_add_u32_e32 v22, 0, v186
	s_and_b32 s20, s31, 12
	s_add_i32 s20, s20, s59
	s_and_b32 s60, s20, 15
	s_or_b32 s63, s61, 3
	s_waitcnt vmcnt(0)
	ds_write_b128 v22, v[2:5]
	ds_write_b128 v22, v[6:9] offset:12800
	v_add_u32_e32 v2, 0, v188
	v_mul_lo_u32 v3, v26, s45
	v_add_u32_e32 v198, v188, v3
	s_lshl_b32 s59, s60, 21
	s_add_u32 s20, s18, s59
	ds_write_b128 v2, v[10:13] offset:256
	v_add_u32_e32 v2, v2, v3
	v_add_u32_e32 v3, 0x6400, v2
	v_add_u32_e32 v2, 0x8600, v2
	ds_write2_b64 v3, v[14:15], v[16:17] offset1:1
	ds_write2_b64 v2, v[18:19], v[20:21] offset1:1
	v_lshlrev_b32_e32 v2, 2, v183
	v_xor_b32_e32 v185, 0x80, v2
	v_lshlrev_b64 v[2:3], 14, v[26:27]
	s_addc_u32 s21, s19, 0
	v_lshl_add_u64 v[190:191], s[20:21], 0, v[2:3]
	s_lshl_b64 s[20:21], s[22:23], 19
	s_add_u32 s20, s20, 0xe002000
	s_addc_u32 s21, s21, 0
	v_lshlrev_b64 v[2:3], 7, v[26:27]
	v_lshl_add_u64 v[192:193], s[20:21], 0, v[2:3]
	s_lshl_b64 s[22:23], s[22:23], 24
	v_lshlrev_b64 v[2:3], 12, v[24:25]
	v_mov_b32_e32 v16, v1
	v_mov_b32_e32 v17, v1
	v_lshlrev_b32_e32 v182, 3, v32
	v_lshlrev_b32_e32 v202, 4, v29
	v_or_b32_e32 v190, v190, v28
	v_or_b32_e32 v192, v192, v28
	v_lshl_add_u64 v[194:195], s[22:23], 0, v[2:3]
	s_lshl_b32 s60, s60, 8
	v_mov_b32_e32 v2, v1
	v_mov_b32_e32 v3, v1
	v_mov_b32_e32 v4, v1
	v_mov_b32_e32 v5, v1
	v_mov_b32_e32 v6, v1
	v_mov_b32_e32 v7, v1
	v_mov_b32_e32 v8, v1
	v_mov_b32_e32 v9, v1
	v_mov_b32_e32 v10, v1
	v_mov_b32_e32 v11, v1
	v_mov_b32_e32 v12, v1
	v_mov_b32_e32 v13, v1
	v_mov_b32_e32 v14, v1
	v_mov_b32_e32 v15, v1
	v_mov_b64_e32 v[32:33], v[16:17]
	v_mov_b64_e32 v[48:49], v[16:17]
	v_mov_b64_e32 v[64:65], v[16:17]
	v_mul_u32_u24_e32 v199, 0x190, v197
	v_mul_u32_u24_e32 v189, 0x88, v197
	v_or3_b32 v194, v194, s60, v0
	v_mov_b32_e32 v170, 0xff800000
	v_mov_b64_e32 v[30:31], v[14:15]
	v_mov_b64_e32 v[28:29], v[12:13]
	v_mov_b64_e32 v[26:27], v[10:11]
	v_mov_b64_e32 v[24:25], v[8:9]
	v_mov_b64_e32 v[22:23], v[6:7]
	v_mov_b64_e32 v[20:21], v[4:5]
	v_mov_b64_e32 v[18:19], v[2:3]
	v_mov_b64_e32 v[46:47], v[14:15]
	v_mov_b64_e32 v[44:45], v[12:13]
	v_mov_b64_e32 v[42:43], v[10:11]
	v_mov_b64_e32 v[40:41], v[8:9]
	v_mov_b64_e32 v[38:39], v[6:7]
	v_mov_b64_e32 v[36:37], v[4:5]
	v_mov_b64_e32 v[34:35], v[2:3]
	v_mov_b64_e32 v[62:63], v[14:15]
	v_mov_b64_e32 v[60:61], v[12:13]
	v_mov_b64_e32 v[58:59], v[10:11]
	v_mov_b64_e32 v[56:57], v[8:9]
	v_mov_b64_e32 v[54:55], v[6:7]
	v_mov_b64_e32 v[52:53], v[4:5]
	v_mov_b64_e32 v[50:51], v[2:3]
	v_mov_b32_e32 v187, 0
	s_mov_b32 s64, s5
	s_waitcnt lgkmcnt(0)
	s_barrier
	v_mov_b32_e32 v216, 0
	v_mov_b32_e32 v217, 0
	v_mov_b32_e32 v218, 0
	v_mov_b32_e32 v219, 0
	v_mov_b32_e32 v220, 0
	v_mov_b32_e32 v221, 0
	v_mov_b32_e32 v222, 0
	v_mov_b32_e32 v223, 0
	v_mov_b32_e32 v224, 0
	v_mov_b32_e32 v225, 0
	v_mov_b32_e32 v226, 0
	v_mov_b32_e32 v227, 0
	v_mov_b32_e32 v228, 0
	v_mov_b32_e32 v229, 0
	v_mov_b32_e32 v230, 0
	v_mov_b32_e32 v231, 0
	s_add_u32 s70, s24, 0x11140000
	s_addc_u32 s71, s25, 0
	s_add_u32 s72, s24, 0x11160000
	s_addc_u32 s73, s25, 0
	s_add_u32 s74, s24, 0x13100000
	s_addc_u32 s75, s25, 0
	s_add_u32 s76, s24, 0x13200000
	s_addc_u32 s77, s25, 0
	s_mov_b64 s[78:79], s[24:25]
	v_add_u32_e32 v238, 0x6400, v198
	v_add_u32_e32 v239, 0x8600, v198
	v_add_u32_e32 v240, 0xa800, v238
	v_add_u32_e32 v241, 0xa800, v239

; DI void attn_unit(LAS unsigned char* lds, int wid, int b, int h, int qb) {
;     ...
;             float ls = 0.f;
; #pragma unroll
;             for (int i = 0; i < 16; ++i) { s0[i] = __builtin_amdgcn_exp2f(s0[i] - mnew); s1[i] = __builtin_amdgcn_exp2f(s1[i] - mnew); ls += s0[i] + s1[i]; }
.LBB0_1082:
	v_exp_f32_e32 v66, v66
	v_exp_f32_e32 v82, v82
	v_exp_f32_e32 v67, v67
	v_exp_f32_e32 v83, v83
	v_exp_f32_e32 v68, v68
	v_exp_f32_e32 v84, v84
	v_exp_f32_e32 v69, v69
	v_exp_f32_e32 v85, v85
	v_add_f32_e32 v208, v82, v66
	v_exp_f32_e32 v70, v70
	v_exp_f32_e32 v86, v86

; DI unsigned pk2(float a, float b) { f32x2 f = {a, b}; bf16v2 r = __builtin_convertvector(f, bf16v2); return __builtin_bit_cast(unsigned, r); }
; #define VLD(dst, j, dt) do { LAS unsigned char* va_ = vb + (32 * (dt) + n) * VROW + (16 * (j) + 4 * g) * 2; const u32x2 lo_ = *(const LAS u32x2*)(va_), hi_ = *(const LAS u32x2*)(va_ + 16); dst = (u32x4){lo_.x, lo_.y, hi_.x, hi_.y}; } while (0)
; DI void attn_unit(LAS unsigned char* lds, int wid, int b, int h, int qb) {
;     ...
;             for (int i = 0; i < 16; ++i) { s0[i] = __builtin_amdgcn_exp2f(s0[i] - mnew); s1[i] = __builtin_amdgcn_exp2f(s1[i] - mnew); ls += s0[i] + s1[i]; }
;             lrow = lrow * alpha + ls;
;             if (__builtin_amdgcn_ballot_w64(alpha != 1.f) != 0ull) {
; #pragma unroll
;                 for (int dt = 0; dt < 4; ++dt)
; #pragma unroll
;                     for (int i = 0; i < 16; ++i) o[dt][i] *= alpha;
;             }
;             bf16x8 pf[4];
; #pragma unroll
;             for (int jj = 0; jj < 2; ++jj) { u32x4 w0, w1;
;                 w0.x = pk2(s0[8 * jj + 0], s0[8 * jj + 1]); w0.y = pk2(s0[8 * jj + 2], s0[8 * jj + 3]); w0.z = pk2(s0[8 * jj + 4], s0[8 * jj + 5]); w0.w = pk2(s0[8 * jj + 6], s0[8 * jj + 7]);
;                 w1.x = pk2(s1[8 * jj + 0], s1[8 * jj + 1]); w1.y = pk2(s1[8 * jj + 2], s1[8 * jj + 3]); w1.z = pk2(s1[8 * jj + 4], s1[8 * jj + 5]); w1.w = pk2(s1[8 * jj + 6], s1[8 * jj + 7]);
;                 pf[jj] = __builtin_bit_cast(bf16x8, w0); pf[2 + jj] = __builtin_bit_cast(bf16x8, w1); }
; #pragma unroll
;             for (int j = 0; j < 4; ++j) {
;                 if (j < 3) {
; #pragma unroll
;                     for (int dt = 0; dt < 4; ++dt) VLD(vf[(j + 1) & 1][dt], j + 1, dt);
;                 }
; #pragma unroll
;                 for (int dt = 0; dt < 4; ++dt) o[dt] = __builtin_amdgcn_mfma_f32_32x32x16_bf16(__builtin_bit_cast(bf16x8, vf[j & 1][dt]), pf[j], o[dt], 0, 0, 0);
;                 __builtin_amdgcn_sched_barrier(0); }
	v_add_f32_e32 v209, v83, v67
	v_exp_f32_e32 v71, v71
	v_exp_f32_e32 v87, v87
	v_add_f32_e32 v208, v209, v208
	v_add_f32_e32 v209, v84, v68
	v_exp_f32_e32 v72, v72
	v_exp_f32_e32 v88, v88
	v_add_f32_e32 v208, v209, v208
	v_add_f32_e32 v209, v85, v69
	v_exp_f32_e32 v73, v73
	v_exp_f32_e32 v89, v89
	v_add_f32_e32 v208, v209, v208
	v_add_f32_e32 v209, v86, v70
	v_exp_f32_e32 v74, v74
	v_exp_f32_e32 v90, v90
	v_add_f32_e32 v208, v209, v208
	v_add_f32_e32 v209, v87, v71
	v_exp_f32_e32 v75, v75
	v_exp_f32_e32 v91, v91
	v_add_f32_e32 v208, v209, v208
	v_add_f32_e32 v209, v88, v72
	v_exp_f32_e32 v76, v76
	v_exp_f32_e32 v92, v92
	v_add_f32_e32 v208, v209, v208
	v_add_f32_e32 v209, v89, v73
	v_exp_f32_e32 v77, v77
	v_exp_f32_e32 v93, v93
	v_add_f32_e32 v208, v209, v208
	v_add_f32_e32 v209, v90, v74
	v_exp_f32_e32 v78, v78
	v_exp_f32_e32 v94, v94
	v_add_f32_e32 v208, v209, v208
	v_add_f32_e32 v209, v91, v75
	v_exp_f32_e32 v79, v79
	v_exp_f32_e32 v95, v95
	v_add_f32_e32 v208, v209, v208
	v_add_f32_e32 v209, v92, v76
	v_exp_f32_e32 v80, v80
	v_exp_f32_e32 v96, v96
	v_add_f32_e32 v208, v209, v208
	v_add_f32_e32 v209, v93, v77
	v_exp_f32_e32 v81, v81
	v_exp_f32_e32 v97, v97
	v_add_f32_e32 v208, v209, v208
	v_add_f32_e32 v209, v94, v78
	v_add_f32_e32 v208, v209, v208
	v_add_f32_e32 v209, v95, v79
	v_add_f32_e32 v208, v209, v208
	v_cvt_pk_bf16_f32 v66, v66, v67
	v_cvt_pk_bf16_f32 v67, v68, v69
	v_cvt_pk_bf16_f32 v68, v70, v71
	v_cvt_pk_bf16_f32 v69, v72, v73
	v_add_f32_e32 v70, v96, v80
	v_add_f32_e32 v70, v70, v208
	v_mfma_f32_32x32x16_bf16 v[50:65], v[166:169], v[66:69], v[50:65]
	v_add_f32_e32 v71, v97, v81
	v_add_f32_e32 v166, v71, v70
	v_cvt_pk_bf16_f32 v70, v82, v83
	v_cvt_pk_bf16_f32 v71, v84, v85
	v_cvt_pk_bf16_f32 v72, v86, v87
	v_cvt_pk_bf16_f32 v73, v88, v89
	v_cvt_pk_bf16_f32 v74, v74, v75
	s_waitcnt lgkmcnt(2)
	v_mfma_f32_32x32x16_bf16 v[34:49], v[178:181], v[66:69], v[34:49]
	v_cvt_pk_bf16_f32 v75, v76, v77
	v_cvt_pk_bf16_f32 v76, v78, v79
	v_cvt_pk_bf16_f32 v77, v80, v81
	v_cvt_pk_bf16_f32 v78, v90, v91
	v_cvt_pk_bf16_f32 v79, v92, v93
	v_cvt_pk_bf16_f32 v80, v94, v95
	v_cvt_pk_bf16_f32 v81, v96, v97
	s_waitcnt lgkmcnt(1)
	v_mfma_f32_32x32x16_bf16 v[18:33], v[174:177], v[66:69], v[18:33]
	ds_read2_b64 v[82:85], v204 offset0:132 offset1:134
	ds_read2_b64 v[86:89], v205 offset0:164 offset1:166
	ds_read2_b64 v[90:93], v206 offset0:196 offset1:198
	ds_read2_b64 v[94:97], v207 offset0:228 offset1:230
	v_fmac_f32_e32 v166, v187, v196
	s_waitcnt lgkmcnt(4)
	v_mfma_f32_32x32x16_bf16 v[2:17], v[170:173], v[66:69], v[2:17]
	s_waitcnt lgkmcnt(3)
	v_mfma_f32_32x32x16_bf16 v[50:65], v[82:85], v[74:77], v[50:65]
	s_waitcnt lgkmcnt(2)
	v_mfma_f32_32x32x16_bf16 v[34:49], v[86:89], v[74:77], v[34:49]
	s_waitcnt lgkmcnt(1)
	v_mfma_f32_32x32x16_bf16 v[18:33], v[90:93], v[74:77], v[18:33]
	ds_read2_b64 v[66:69], v204 offset0:136 offset1:138
	ds_read2_b64 v[82:85], v205 offset0:168 offset1:170
	ds_read2_b64 v[86:89], v206 offset0:200 offset1:202
	ds_read2_b64 v[90:93], v207 offset0:232 offset1:234
	s_waitcnt lgkmcnt(4)
	v_mfma_f32_32x32x16_bf16 v[2:17], v[94:97], v[74:77], v[2:17]
	s_waitcnt lgkmcnt(3)
	v_mfma_f32_32x32x16_bf16 v[50:65], v[66:69], v[70:73], v[50:65]
	s_waitcnt lgkmcnt(2)
	v_mfma_f32_32x32x16_bf16 v[34:49], v[82:85], v[70:73], v[34:49]
	s_waitcnt lgkmcnt(1)
	v_mfma_f32_32x32x16_bf16 v[18:33], v[86:89], v[70:73], v[18:33]
	ds_read2_b64 v[66:69], v204 offset0:140 offset1:142
	ds_read2_b64 v[74:77], v205 offset0:172 offset1:174
	ds_read2_b64 v[82:85], v206 offset0:204 offset1:206
	ds_read2_b64 v[86:89], v207 offset0:236 offset1:238
	s_waitcnt lgkmcnt(4)
	v_mfma_f32_32x32x16_bf16 v[2:17], v[90:93], v[70:73], v[2:17]
	s_waitcnt lgkmcnt(3)
	v_mfma_f32_32x32x16_bf16 v[50:65], v[66:69], v[78:81], v[50:65]
	s_waitcnt lgkmcnt(2)
	v_mfma_f32_32x32x16_bf16 v[34:49], v[74:77], v[78:81], v[34:49]
	s_waitcnt lgkmcnt(1)
	v_mfma_f32_32x32x16_bf16 v[18:33], v[82:85], v[78:81], v[18:33]
	s_waitcnt lgkmcnt(0)
	v_mfma_f32_32x32x16_bf16 v[2:17], v[86:89], v[78:81], v[2:17]
	v_mov_b32_e32 v187, v166
	s_branch .LBB0_1084

; DI void attn_unit(LAS unsigned char* lds, int wid, int b, int h, int qb) {
;     ...
;         if (kt + 1 < nkt) A_WRITE(buf ^ 1);
;         __syncthreads();
.LBB0_1084:
	s_add_u32 s70, s70, 0x40000
	s_addc_u32 s71, s71, 0
	s_add_u32 s72, s72, 0x40000
	s_addc_u32 s73, s73, 0
	s_add_u32 s78, s78, 0x2000
	s_addc_u32 s79, s79, 0
	s_add_u32 s74, s74, 0x80
	s_addc_u32 s75, s75, 0
	s_add_u32 s76, s76, 0x80
	s_addc_u32 s77, s77, 0
	s_add_i32 s64, s64, 1
	s_cmp_lg_u32 s65, 0
	s_cbranch_scc1 .Lw1_b0
	s_waitcnt vmcnt(4)
	ds_write_b128 v186, v[146:149] offset:43008
	s_waitcnt vmcnt(3)
	ds_write_b128 v186, v[150:153] offset:55808
	s_waitcnt vmcnt(2)
	ds_write_b128 v188, v[154:157] offset:43264
	s_waitcnt vmcnt(1)
	ds_write2_b64 v240, v[158:159], v[160:161] offset1:1
	s_waitcnt vmcnt(0)
	ds_write2_b64 v241, v[162:163], v[164:165] offset1:1
	s_branch .Lw1_join
.Lw1_b0:
	s_waitcnt vmcnt(4)
	ds_write_b128 v186, v[146:149] offset:0
	s_waitcnt vmcnt(3)
	ds_write_b128 v186, v[150:153] offset:12800
	s_waitcnt vmcnt(2)
	ds_write_b128 v188, v[154:157] offset:256
	s_waitcnt vmcnt(1)
	ds_write2_b64 v238, v[158:159], v[160:161] offset1:1
	s_waitcnt vmcnt(0)
	ds_write2_b64 v239, v[162:163], v[164:165] offset1:1
.Lw1_join:
	s_cmp_eq_u32 s63, s64
	s_waitcnt lgkmcnt(0)
	s_barrier
	s_cbranch_scc1 .LBB0_1086
	v_mov_b32_e32 v170, v203
	s_branch .LBB0_1079

; DI void attn_unit(LAS unsigned char* lds, int wid, int b, int h, int qb) {
;     ...
;             float ls = 0.f;
; #pragma unroll
;             for (int i = 0; i < 16; ++i) { s0[i] = __builtin_amdgcn_exp2f(s0[i] - mnew); s1[i] = __builtin_amdgcn_exp2f(s1[i] - mnew); ls += s0[i] + s1[i]; }
.LBB0_1089:
	v_exp_f32_e32 v66, v66
	v_exp_f32_e32 v82, v82
	v_exp_f32_e32 v67, v67
	v_exp_f32_e32 v83, v83
	v_exp_f32_e32 v68, v68
	v_exp_f32_e32 v84, v84
	v_exp_f32_e32 v69, v69
	v_exp_f32_e32 v85, v85
	v_add_f32_e32 v120, v82, v66
	v_exp_f32_e32 v70, v70
	v_exp_f32_e32 v86, v86

; #define LAS __attribute__((address_space(3)))
; DI unsigned pk2(float a, float b) { f32x2 f = {a, b}; bf16v2 r = __builtin_convertvector(f, bf16v2); return __builtin_bit_cast(unsigned, r); }
; DI void attn_unit(LAS unsigned char* lds, int wid, int b, int h, int qb) {
;     ...
;             for (int i = 0; i < 16; ++i) { s0[i] = __builtin_amdgcn_exp2f(s0[i] - mnew); s1[i] = __builtin_amdgcn_exp2f(s1[i] - mnew); ls += s0[i] + s1[i]; }
;             lrow = lrow * alpha + ls;
;             if (__builtin_amdgcn_ballot_w64(alpha != 1.f) != 0ull) {
; #pragma unroll
;                 for (int dt = 0; dt < 4; ++dt)
; #pragma unroll
;                     for (int i = 0; i < 16; ++i) o[dt][i] *= alpha;
;             }
;             bf16x8 pf[4];
; #pragma unroll
;             for (int jj = 0; jj < 2; ++jj) { u32x4 w0, w1;
;                 w0.x = pk2(s0[8 * jj + 0], s0[8 * jj + 1]); w0.y = pk2(s0[8 * jj + 2], s0[8 * jj + 3]); w0.z = pk2(s0[8 * jj + 4], s0[8 * jj + 5]); w0.w = pk2(s0[8 * jj + 6], s0[8 * jj + 7]);
;                 w1.x = pk2(s1[8 * jj + 0], s1[8 * jj + 1]); w1.y = pk2(s1[8 * jj + 2], s1[8 * jj + 3]); w1.z = pk2(s1[8 * jj + 4], s1[8 * jj + 5]); w1.w = pk2(s1[8 * jj + 6], s1[8 * jj + 7]);
;                 pf[jj] = __builtin_bit_cast(bf16x8, w0); pf[2 + jj] = __builtin_bit_cast(bf16x8, w1); }
; #pragma unroll
;             for (int j = 0; j < 4; ++j) {
;                 if (j < 3) {
; #pragma unroll
;                     for (int dt = 0; dt < 4; ++dt) VLD(vf[(j + 1) & 1][dt], j + 1, dt);
;                 }
; #pragma unroll
;                 for (int dt = 0; dt < 4; ++dt) o[dt] = __builtin_amdgcn_mfma_f32_32x32x16_bf16(__builtin_bit_cast(bf16x8, vf[j & 1][dt]), pf[j], o[dt], 0, 0, 0);
;                 __builtin_amdgcn_sched_barrier(0); }
;     ...
;         }
;         if (kt + 1 < nkt) A_WRITE(buf ^ 1);
;         __syncthreads();
;     }
;     ...
;     const float lt = lrow + shfl_xor_l(lrow, lane, 32), inv = 1.f / lt;
;     LAS unsigned char* pt_ = lds + ABUF + wid * (32 * 272);
; #pragma unroll
;     for (int dt = 0; dt < 4; ++dt)
; #pragma unroll
;         for (int blk = 0; blk < 4; ++blk) { const f32x4 v = {o[dt][4 * blk] * inv, o[dt][4 * blk + 1] * inv, o[dt][4 * blk + 2] * inv, o[dt][4 * blk + 3] * inv};
;             *(LAS u32x2*)(pt_ + n * 272 + (32 * dt + 8 * blk + 4 * g) * 2) = pk4(v); }
	v_add_f32_e32 v121, v83, v67
	v_exp_f32_e32 v71, v71
	v_exp_f32_e32 v87, v87
	v_add_f32_e32 v120, v121, v120
	v_add_f32_e32 v121, v84, v68
	v_exp_f32_e32 v72, v72
	v_exp_f32_e32 v88, v88
	v_add_f32_e32 v120, v121, v120
	v_add_f32_e32 v121, v85, v69
	v_exp_f32_e32 v73, v73
	v_exp_f32_e32 v89, v89
	v_add_f32_e32 v120, v121, v120
	v_add_f32_e32 v121, v86, v70
	v_exp_f32_e32 v74, v74
	v_exp_f32_e32 v90, v90
	v_add_f32_e32 v120, v121, v120
	v_add_f32_e32 v121, v87, v71
	v_exp_f32_e32 v75, v75
	v_exp_f32_e32 v91, v91
	v_add_f32_e32 v120, v121, v120
	v_add_f32_e32 v121, v88, v72
	v_exp_f32_e32 v76, v76
	v_exp_f32_e32 v92, v92
	v_add_f32_e32 v120, v121, v120
	v_add_f32_e32 v121, v89, v73
	v_exp_f32_e32 v77, v77
	v_exp_f32_e32 v93, v93
	v_add_f32_e32 v120, v121, v120
	v_add_f32_e32 v121, v90, v74
	v_exp_f32_e32 v78, v78
	v_exp_f32_e32 v94, v94
	v_add_f32_e32 v120, v121, v120
	v_add_f32_e32 v121, v91, v75
	v_exp_f32_e32 v79, v79
	v_exp_f32_e32 v95, v95
	v_add_f32_e32 v120, v121, v120
	v_add_f32_e32 v121, v92, v76
	v_exp_f32_e32 v80, v80
	v_exp_f32_e32 v96, v96
	v_add_f32_e32 v120, v121, v120
	v_add_f32_e32 v121, v93, v77
	v_exp_f32_e32 v81, v81
	v_exp_f32_e32 v97, v97
	v_add_f32_e32 v120, v121, v120
	v_add_f32_e32 v121, v94, v78
	v_add_f32_e32 v120, v121, v120
	v_add_f32_e32 v121, v95, v79
	v_add_f32_e32 v120, v121, v120
	v_cvt_pk_bf16_f32 v66, v66, v67
	v_cvt_pk_bf16_f32 v67, v68, v69
	v_cvt_pk_bf16_f32 v68, v70, v71
	v_cvt_pk_bf16_f32 v69, v72, v73
	v_add_f32_e32 v70, v96, v80
	v_add_f32_e32 v70, v70, v120
	v_mfma_f32_32x32x16_bf16 v[50:65], v[102:105], v[66:69], v[50:65]
	v_add_f32_e32 v71, v97, v81
	v_add_f32_e32 v102, v71, v70
	v_cvt_pk_bf16_f32 v70, v82, v83
	v_cvt_pk_bf16_f32 v71, v84, v85
	v_cvt_pk_bf16_f32 v72, v86, v87
	v_cvt_pk_bf16_f32 v73, v88, v89
	v_cvt_pk_bf16_f32 v74, v74, v75
	v_mfma_f32_32x32x16_bf16 v[34:49], v[110:113], v[66:69], v[34:49]
	v_cvt_pk_bf16_f32 v75, v76, v77
	v_cvt_pk_bf16_f32 v76, v78, v79
	v_cvt_pk_bf16_f32 v77, v80, v81
	v_cvt_pk_bf16_f32 v78, v90, v91
	v_cvt_pk_bf16_f32 v79, v92, v93
	v_cvt_pk_bf16_f32 v80, v94, v95
	v_cvt_pk_bf16_f32 v81, v96, v97
	s_waitcnt lgkmcnt(1)
	v_mfma_f32_32x32x16_bf16 v[18:33], v[106:109], v[66:69], v[18:33]
	ds_read2_b64 v[82:85], v115 offset0:132 offset1:134
	ds_read2_b64 v[86:89], v116 offset0:164 offset1:166
	ds_read2_b64 v[90:93], v117 offset0:196 offset1:198
	ds_read2_b64 v[94:97], v118 offset0:228 offset1:230
	v_fmac_f32_e32 v102, v187, v114
	s_waitcnt lgkmcnt(4)
	v_mfma_f32_32x32x16_bf16 v[2:17], v[98:101], v[66:69], v[2:17]
	s_waitcnt lgkmcnt(3)
	v_mfma_f32_32x32x16_bf16 v[50:65], v[82:85], v[74:77], v[50:65]
	s_waitcnt lgkmcnt(2)
	v_mfma_f32_32x32x16_bf16 v[34:49], v[86:89], v[74:77], v[34:49]
	s_waitcnt lgkmcnt(1)
	v_mfma_f32_32x32x16_bf16 v[18:33], v[90:93], v[74:77], v[18:33]
	ds_read2_b64 v[66:69], v115 offset0:136 offset1:138
	ds_read2_b64 v[82:85], v116 offset0:168 offset1:170
	ds_read2_b64 v[86:89], v117 offset0:200 offset1:202
	ds_read2_b64 v[90:93], v118 offset0:232 offset1:234
	s_waitcnt lgkmcnt(4)
	v_mfma_f32_32x32x16_bf16 v[2:17], v[94:97], v[74:77], v[2:17]
	s_waitcnt lgkmcnt(3)
	v_mfma_f32_32x32x16_bf16 v[50:65], v[66:69], v[70:73], v[50:65]
	s_waitcnt lgkmcnt(2)
	v_mfma_f32_32x32x16_bf16 v[34:49], v[82:85], v[70:73], v[34:49]
	s_waitcnt lgkmcnt(1)
	v_mfma_f32_32x32x16_bf16 v[18:33], v[86:89], v[70:73], v[18:33]
	ds_read2_b64 v[66:69], v115 offset0:140 offset1:142
	ds_read2_b64 v[74:77], v116 offset0:172 offset1:174
	ds_read2_b64 v[82:85], v117 offset0:204 offset1:206
	ds_read2_b64 v[86:89], v118 offset0:236 offset1:238
	s_waitcnt lgkmcnt(4)
	v_mfma_f32_32x32x16_bf16 v[2:17], v[90:93], v[70:73], v[2:17]
	s_waitcnt lgkmcnt(3)
	v_mfma_f32_32x32x16_bf16 v[50:65], v[66:69], v[78:81], v[50:65]
	s_waitcnt lgkmcnt(2)
	v_mfma_f32_32x32x16_bf16 v[34:49], v[74:77], v[78:81], v[34:49]
	s_waitcnt lgkmcnt(1)
	v_mfma_f32_32x32x16_bf16 v[18:33], v[82:85], v[78:81], v[18:33]
	s_waitcnt lgkmcnt(0)
	v_mfma_f32_32x32x16_bf16 v[2:17], v[86:89], v[78:81], v[2:17]
	v_mov_b32_e32 v187, v102
.LBB0_1090:
	ds_bpermute_b32 v66, v185, v187
	s_waitcnt lgkmcnt(0)
	s_barrier
	v_mov_b32_e32 v185, v1
	v_add_f32_e32 v66, v187, v66
	v_div_scale_f32 v67, s[62:63], v66, v66, 1.0
	v_rcp_f32_e32 v68, v67
	v_div_scale_f32 v69, vcc, 1.0, v66, 1.0
	v_mov_b32_e32 v187, v201
	v_fma_f32 v70, -v67, v68, 1.0
	v_fmac_f32_e32 v68, v70, v68
	v_mul_f32_e32 v70, v69, v68
	v_fma_f32 v71, -v67, v70, v69
	v_fmac_f32_e32 v70, v71, v68
	v_fma_f32 v67, -v67, v70, v69
	v_div_fmas_f32 v67, v67, v68, v70
	v_div_fixup_f32 v66, v67, v66, 1.0
	v_mul_u32_u24_e32 v67, 0x110, v197
	v_add3_u32 v67, s30, v67, v184
	v_pk_mul_f32 v[2:3], v[2:3], v[66:67] op_sel_hi:[1,0]
	v_pk_mul_f32 v[4:5], v[4:5], v[66:67] op_sel_hi:[1,0]
	v_pk_mul_f32 v[50:51], v[50:51], v[66:67] op_sel_hi:[1,0]
	v_pk_mul_f32 v[52:53], v[52:53], v[66:67] op_sel_hi:[1,0]
	v_cvt_pk_bf16_f32 v2, v2, v3
	v_cvt_pk_bf16_f32 v3, v4, v5
	v_pk_mul_f32 v[4:5], v[6:7], v[66:67] op_sel_hi:[1,0]
	v_pk_mul_f32 v[6:7], v[8:9], v[66:67] op_sel_hi:[1,0]
	v_cvt_pk_bf16_f32 v50, v50, v51
	v_cvt_pk_bf16_f32 v51, v52, v53
	v_pk_mul_f32 v[52:53], v[54:55], v[66:67] op_sel_hi:[1,0]
	v_pk_mul_f32 v[54:55], v[56:57], v[66:67] op_sel_hi:[1,0]
	v_add_u32_e32 v56, 0xa800, v67
	v_cvt_pk_bf16_f32 v4, v4, v5
	v_cvt_pk_bf16_f32 v5, v6, v7
	ds_write2_b64 v56, v[2:3], v[4:5] offset0:24 offset1:26
	v_pk_mul_f32 v[2:3], v[10:11], v[66:67] op_sel_hi:[1,0]
	v_pk_mul_f32 v[4:5], v[12:13], v[66:67] op_sel_hi:[1,0]
	v_pk_mul_f32 v[34:35], v[34:35], v[66:67] op_sel_hi:[1,0]
	v_pk_mul_f32 v[36:37], v[36:37], v[66:67] op_sel_hi:[1,0]
	v_pk_mul_f32 v[18:19], v[18:19], v[66:67] op_sel_hi:[1,0]
; #define LAS __attribute__((address_space(3)))
; DI u32x2 pk4(f32x4 v) { u32x2 r; r.x = pk2(v[0], v[1]); r.y = pk2(v[2], v[3]); return r; }
; DI int lane_id() { int l = __builtin_amdgcn_mbcnt_hi(-1, __builtin_amdgcn_mbcnt_lo(-1, 0)); asm volatile("" : "+v"(l)); return l; }
; DI void attn_unit(LAS unsigned char* lds, int wid, int b, int h, int qb) {
;     ...
;     const int lane = lane_id(), tid = wid * 64 + lane, n = lane & 31, g = lane >> 5;
;     const int q0 = qb * 256 + wid * 32, cq = q0 >> 6, nkt = 4 * qb + 4;
;     const size_t tokq = (size_t)b * SEQ + q0 + n;
;     const bf16_t* Q = WSB(OFF_Q); const bf16_t* KN = WSB(OFF_KN); const bf16_t* KR = WSB(OFF_KR); const bf16_t* VT = WSB(OFF_VT2);
;     bf16x8 qf[12];
; #pragma unroll
;     for (int ks = 0; ks < 12; ++ks) qf[ks] = *(const bf16x8*)(Q + tokq * 3072 + h * 192 + ks * 16 + g * 8);
;     f32x16 o[4];
; #pragma unroll
;     for (int dt = 0; dt < 4; ++dt)
; #pragma unroll
;         for (int i = 0; i < 16; ++i) o[dt][i] = 0.f;
;     float mrow = -__builtin_inff(), lrow = 0.f;
;     const int krow = tid >> 4, kc16 = tid & 15, rrow = tid >> 3, rc8 = tid & 7;
;     const bf16_t* kn_src = KN + ((size_t)b * SEQ + krow) * 2048 + h * 128 + kc16 * 8;
;     const bf16_t* kr_src = KR + ((size_t)b * SEQ + rrow) * 64 + rc8 * 8;
;     const bf16_t* v_src = VT + ((size_t)h * 128 + rrow) * 8192 + (size_t)b * SEQ + rc8 * 8;
;     const int kn_dst = krow * KROW + kc16 * 16, kr_dst = rrow * KROW + 256 + rc8 * 16, v_dst = KBYTES + rrow * VROW + rc8 * 16;
;     ...
;     for (int dt = 0; dt < 4; ++dt)
; #pragma unroll
;         for (int blk = 0; blk < 4; ++blk) { const f32x4 v = {o[dt][4 * blk] * inv, o[dt][4 * blk + 1] * inv, o[dt][4 * blk + 2] * inv, o[dt][4 * blk + 3] * inv};
;             *(LAS u32x2*)(pt_ + n * 272 + (32 * dt + 8 * blk + 4 * g) * 2) = pk4(v); }
;     asm volatile("" ::: "memory");
;     bf16_t* od = WSB(OFF_O) + ((size_t)b * SEQ + q0 + (lane >> 4)) * 2048 + h * 128 + (lane & 15) * 8;
; #pragma unroll
;     for (int j = 0; j < 8; ++j) { const u32x4 w = *(const LAS u32x4*)(pt_ + (4 * j + (lane >> 4)) * 272 + (lane & 15) * 16); *(u32x4*)(od + (size_t)(4 * j) * 2048) = w; }
;     asm volatile("" ::: "memory");
	v_pk_mul_f32 v[20:21], v[20:21], v[66:67] op_sel_hi:[1,0]
	v_cvt_pk_bf16_f32 v2, v2, v3
	v_cvt_pk_bf16_f32 v3, v4, v5
	v_pk_mul_f32 v[4:5], v[14:15], v[66:67] op_sel_hi:[1,0]
	v_pk_mul_f32 v[6:7], v[16:17], v[66:67] op_sel_hi:[1,0]
	v_cvt_pk_bf16_f32 v34, v34, v35
	v_cvt_pk_bf16_f32 v35, v36, v37
	v_pk_mul_f32 v[36:37], v[38:39], v[66:67] op_sel_hi:[1,0]
	v_pk_mul_f32 v[38:39], v[40:41], v[66:67] op_sel_hi:[1,0]
	v_cvt_pk_bf16_f32 v18, v18, v19
	v_cvt_pk_bf16_f32 v19, v20, v21
	v_pk_mul_f32 v[20:21], v[22:23], v[66:67] op_sel_hi:[1,0]
	v_pk_mul_f32 v[22:23], v[24:25], v[66:67] op_sel_hi:[1,0]
	v_cvt_pk_bf16_f32 v4, v4, v5
	v_cvt_pk_bf16_f32 v5, v6, v7
	v_cvt_pk_bf16_f32 v52, v52, v53
	v_cvt_pk_bf16_f32 v53, v54, v55
	v_cvt_pk_bf16_f32 v36, v36, v37
	v_cvt_pk_bf16_f32 v37, v38, v39
	v_cvt_pk_bf16_f32 v20, v20, v21
	v_cvt_pk_bf16_f32 v21, v22, v23
	ds_write2_b64 v56, v[2:3], v[4:5] offset0:28 offset1:30
	v_ashrrev_i32_e32 v2, 4, v183
	ds_write2_b64 v56, v[50:51], v[52:53] offset1:2
	v_pk_mul_f32 v[50:51], v[58:59], v[66:67] op_sel_hi:[1,0]
	v_pk_mul_f32 v[52:53], v[60:61], v[66:67] op_sel_hi:[1,0]
	ds_write2_b64 v56, v[34:35], v[36:37] offset0:8 offset1:10
	v_pk_mul_f32 v[34:35], v[42:43], v[66:67] op_sel_hi:[1,0]
	v_pk_mul_f32 v[36:37], v[44:45], v[66:67] op_sel_hi:[1,0]
	ds_write2_b64 v56, v[18:19], v[20:21] offset0:16 offset1:18
	v_pk_mul_f32 v[18:19], v[26:27], v[66:67] op_sel_hi:[1,0]
	v_pk_mul_f32 v[20:21], v[28:29], v[66:67] op_sel_hi:[1,0]
	v_ashrrev_i32_e32 v3, 31, v2
	v_cvt_pk_bf16_f32 v50, v50, v51
	v_cvt_pk_bf16_f32 v51, v52, v53
	v_pk_mul_f32 v[52:53], v[62:63], v[66:67] op_sel_hi:[1,0]
	v_pk_mul_f32 v[54:55], v[64:65], v[66:67] op_sel_hi:[1,0]
	v_cvt_pk_bf16_f32 v34, v34, v35
	v_cvt_pk_bf16_f32 v35, v36, v37
	v_pk_mul_f32 v[36:37], v[46:47], v[66:67] op_sel_hi:[1,0]
	v_pk_mul_f32 v[38:39], v[48:49], v[66:67] op_sel_hi:[1,0]
	v_cvt_pk_bf16_f32 v18, v18, v19
	v_cvt_pk_bf16_f32 v19, v20, v21
	v_pk_mul_f32 v[20:21], v[30:31], v[66:67] op_sel_hi:[1,0]
	v_pk_mul_f32 v[22:23], v[32:33], v[66:67] op_sel_hi:[1,0]
	v_lshl_add_u64 v[4:5], s[26:27], 0, v[2:3]
	v_cvt_pk_bf16_f32 v52, v52, v53
	v_cvt_pk_bf16_f32 v53, v54, v55
	v_cvt_pk_bf16_f32 v36, v36, v37
	v_cvt_pk_bf16_f32 v37, v38, v39
	v_cvt_pk_bf16_f32 v20, v20, v21
	v_cvt_pk_bf16_f32 v21, v22, v23
	v_lshlrev_b64 v[4:5], 12, v[4:5]
	ds_write2_b64 v56, v[50:51], v[52:53] offset0:4 offset1:6
	ds_write2_b64 v56, v[34:35], v[36:37] offset0:12 offset1:14
	ds_write2_b64 v56, v[18:19], v[20:21] offset0:20 offset1:22
	v_lshl_add_u64 v[4:5], s[24:25], 0, v[4:5]
	s_lshl_b32 s24, s4, 1
	s_mov_b32 s25, s5
	v_mul_lo_u32 v2, v2, s46
	v_lshl_add_u64 v[4:5], v[4:5], 0, s[24:25]
	v_lshlrev_b32_e32 v6, 1, v182
	v_mov_b32_e32 v7, v1
	v_add3_u32 v0, s30, v0, v2
	v_lshl_add_u64 v[10:11], v[4:5], 0, v[6:7]
	ds_read_b128 v[2:5], v0 offset:43008
	ds_read_b128 v[6:9], v0 offset:44096
	v_add_co_u32_e32 v12, vcc, s47, v10
	s_mov_b64 s[26:27], s[0:1]
	s_nop 0
	v_addc_co_u32_e32 v13, vcc, 0, v11, vcc
	s_waitcnt lgkmcnt(1)
	global_store_dwordx4 v[12:13], v[2:5], off
	v_mov_b32_e32 v172, 0xff800000
	s_nop 0
	v_add_co_u32_e32 v2, vcc, s48, v10
	s_nop 1
	v_addc_co_u32_e32 v3, vcc, 0, v11, vcc
	s_waitcnt lgkmcnt(0)
	global_store_dwordx4 v[2:3], v[6:9], off
	ds_read_b128 v[2:5], v0 offset:45184
	ds_read_b128 v[6:9], v0 offset:46272
	v_add_co_u32_e32 v12, vcc, s49, v10
	s_nop 1
	v_addc_co_u32_e32 v13, vcc, 0, v11, vcc
	s_waitcnt lgkmcnt(1)
	global_store_dwordx4 v[12:13], v[2:5], off
	s_nop 1
	v_add_co_u32_e32 v2, vcc, s50, v10
	s_nop 1
	v_addc_co_u32_e32 v3, vcc, 0, v11, vcc
	s_waitcnt lgkmcnt(0)
	global_store_dwordx4 v[2:3], v[6:9], off
	ds_read_b128 v[2:5], v0 offset:47360
	ds_read_b128 v[6:9], v0 offset:48448
	v_add_co_u32_e32 v12, vcc, s51, v10
	s_nop 1
	v_addc_co_u32_e32 v13, vcc, 0, v11, vcc
	s_waitcnt lgkmcnt(1)
	global_store_dwordx4 v[12:13], v[2:5], off
	s_nop 1
	v_add_co_u32_e32 v2, vcc, s52, v10
	s_nop 1
	v_addc_co_u32_e32 v3, vcc, 0, v11, vcc
	s_waitcnt lgkmcnt(0)
	global_store_dwordx4 v[2:3], v[6:9], off
	ds_read_b128 v[2:5], v0 offset:49536
	ds_read_b128 v[6:9], v0 offset:50624
	v_add_co_u32_e32 v12, vcc, s53, v10
	s_nop 1
	v_addc_co_u32_e32 v13, vcc, 0, v11, vcc
	s_waitcnt lgkmcnt(1)
	global_store_dwordx4 v[12:13], v[2:5], off
	s_nop 1
	v_add_co_u32_e32 v2, vcc, s54, v10
	s_nop 1
	v_addc_co_u32_e32 v3, vcc, 0, v11, vcc
	s_waitcnt lgkmcnt(0)
	global_store_dwordx4 v[2:3], v[6:9], off
	s_load_dwordx2 s[26:27], s[26:27], 0xa8
	v_add_u32_e32 v0, s28, v187
	v_ashrrev_i32_e32 v24, 3, v0
	v_ashrrev_i32_e32 v25, 31, v24
	v_ashrrev_i32_e32 v22, 4, v0
	v_lshl_add_u64 v[4:5], s[16:17], 0, v[24:25]
	v_ashrrev_i32_e32 v23, 31, v22
	v_lshlrev_b64 v[4:5], 7, v[4:5]
	v_lshlrev_b32_e32 v0, 4, v187
	v_lshl_add_u64 v[2:3], s[16:17], 0, v[22:23]
	s_waitcnt lgkmcnt(0)
; DI int lane_id() { int l = __builtin_amdgcn_mbcnt_hi(-1, __builtin_amdgcn_mbcnt_lo(-1, 0)); asm volatile("" : "+v"(l)); return l; }
; #define A_LOAD(kt) do { const size_t ko = (size_t)(kt) * 64; st0 = *(const u32x4*)(kn_src + ko * 2048); st1 = *(const u32x4*)(kn_src + (ko + 32) * 2048); \
;         st2 = *(const u32x4*)(kr_src + ko * 64); st3 = *(const u32x4*)(v_src + ko); st4 = *(const u32x4*)(v_src + ko + (size_t)64 * 8192); } while (0)
; DI void attn_unit(LAS unsigned char* lds, int wid, int b, int h, int qb) {
;     ...
;     const int lane = lane_id(), tid = wid * 64 + lane, n = lane & 31, g = lane >> 5;
;     const int q0 = qb * 256 + wid * 32, cq = q0 >> 6, nkt = 4 * qb + 4;
;     const size_t tokq = (size_t)b * SEQ + q0 + n;
;     const bf16_t* Q = WSB(OFF_Q); const bf16_t* KN = WSB(OFF_KN); const bf16_t* KR = WSB(OFF_KR); const bf16_t* VT = WSB(OFF_VT2);
;     bf16x8 qf[12];
; #pragma unroll
;     for (int ks = 0; ks < 12; ++ks) qf[ks] = *(const bf16x8*)(Q + tokq * 3072 + h * 192 + ks * 16 + g * 8);
;     f32x16 o[4];
; #pragma unroll
;     for (int dt = 0; dt < 4; ++dt)
; #pragma unroll
;         for (int i = 0; i < 16; ++i) o[dt][i] = 0.f;
;     float mrow = -__builtin_inff(), lrow = 0.f;
;     const int krow = tid >> 4, kc16 = tid & 15, rrow = tid >> 3, rc8 = tid & 7;
;     const bf16_t* kn_src = KN + ((size_t)b * SEQ + krow) * 2048 + h * 128 + kc16 * 8;
;     const bf16_t* kr_src = KR + ((size_t)b * SEQ + rrow) * 64 + rc8 * 8;
;     const bf16_t* v_src = VT + ((size_t)h * 128 + rrow) * 8192 + (size_t)b * SEQ + rc8 * 8;
;     const int kn_dst = krow * KROW + kc16 * 16, kr_dst = rrow * KROW + 256 + rc8 * 16, v_dst = KBYTES + rrow * VROW + rc8 * 16;
;     u32x4 st0, st1, st2, st3, st4;
;     ...
;     A_LOAD(0); A_WRITE(0); __syncthreads();
	v_lshl_add_u64 v[4:5], s[26:27], 0, v[4:5]
	v_and_b32_e32 v0, 0x70, v0
	v_lshlrev_b64 v[2:3], 12, v[2:3]
	v_lshl_add_u64 v[10:11], v[4:5], 0, v[0:1]
	v_lshl_add_u64 v[4:5], v[24:25], 0, s[4:5]
	v_and_b32_e32 v30, 15, v187
	v_lshl_add_u64 v[2:3], s[26:27], 0, v[2:3]
	v_lshlrev_b64 v[4:5], 14, v[4:5]
	v_lshl_add_u64 v[2:3], v[2:3], 0, s[24:25]
	v_lshlrev_b32_e32 v184, 4, v30
	v_lshl_add_u64 v[4:5], s[26:27], 0, v[4:5]
	v_lshl_add_u64 v[2:3], v[2:3], 0, v[184:185]
	v_lshl_add_u64 v[4:5], s[16:17], 1, v[4:5]
	v_lshl_add_u64 v[18:19], v[4:5], 0, v[0:1]
	v_add_co_u32_e32 v4, vcc, s40, v2
	s_and_b32 s4, s57, 7
	s_nop 0
	v_addc_co_u32_e32 v5, vcc, 0, v3, vcc
	v_add_co_u32_e32 v6, vcc, s41, v2
	s_lshl_b32 s4, s4, 2
	s_lshl_b32 s25, s56, 8
	v_addc_co_u32_e32 v7, vcc, 0, v3, vcc
	s_or_b32 s4, s4, 3
	s_add_i32 s25, s25, s29
	v_add_co_u32_e32 v10, vcc, s42, v10
	v_and_b32_e32 v202, 31, v187
	s_add_u32 s16, s16, s25
	v_addc_co_u32_e32 v11, vcc, 0, v11, vcc
	v_or_b32_e32 v28, s16, v202
	v_mov_b64_e32 v[26:27], s[26:27]
	v_add_co_u32_e32 v14, vcc, s43, v18
	v_ashrrev_i32_e32 v31, 5, v187
	s_addc_u32 s17, s17, 0
	v_mad_u64_u32 v[26:27], s[62:63], v28, s37, v[26:27]
	v_addc_co_u32_e32 v15, vcc, 0, v19, vcc
	v_mad_i32_i24 v27, s17, v200, v27
	s_lshl_b32 s62, s58, 1
	s_mov_b32 s63, s5
	v_lshlrev_b32_e32 v188, 3, v31
	v_add_co_u32_e32 v18, vcc, s44, v18
	v_lshl_add_u64 v[26:27], v[26:27], 0, s[62:63]
	v_ashrrev_i32_e32 v189, 31, v188
	global_load_dwordx4 v[2:5], v[4:5], off
	s_nop 0
	global_load_dwordx4 v[6:9], v[6:7], off
	v_addc_co_u32_e32 v19, vcc, 0, v19, vcc
	v_lshl_add_u64 v[26:27], v[188:189], 1, v[26:27]
	global_load_dwordx4 v[10:13], v[10:11], off
	v_lshl_add_u64 v[28:29], v[26:27], 0, s[8:9]
	v_add_co_u32_e32 v26, vcc, s38, v26
	global_load_dwordx4 v[14:17], v[14:15], off
	s_nop 0
	v_addc_co_u32_e32 v27, vcc, 0, v27, vcc
	global_load_dwordx4 v[18:21], v[18:19], off
	s_nop 0
	global_load_dwordx4 v[152:155], v[28:29], off offset:32
	global_load_dwordx4 v[148:151], v[28:29], off offset:64
	global_load_dwordx4 v[144:147], v[28:29], off offset:96
	global_load_dwordx4 v[140:143], v[28:29], off offset:128
	global_load_dwordx4 v[136:139], v[28:29], off offset:160
	global_load_dwordx4 v[132:135], v[28:29], off offset:192
	global_load_dwordx4 v[128:131], v[28:29], off offset:224
	global_load_dwordx4 v[124:127], v[28:29], off offset:256
	global_load_dwordx4 v[120:123], v[28:29], off offset:288
	global_load_dwordx4 v[116:119], v[28:29], off offset:320
	global_load_dwordx4 v[156:159], v[26:27], off
	global_load_dwordx4 v[112:115], v[28:29], off offset:352
	v_mad_u64_u32 v[190:191], s[62:63], v22, s39, v[184:185]
	v_add_u32_e32 v26, 0, v190
	v_mad_u64_u32 v[192:193], s[62:63], v24, s39, v[0:1]
	s_waitcnt vmcnt(16)
	ds_write_b128 v26, v[2:5]
	s_waitcnt vmcnt(15)
	ds_write_b128 v26, v[6:9] offset:12800
	v_add_u32_e32 v2, 0, v192
	v_mul_lo_u32 v3, v24, s45
	s_lshr_b32 s25, s25, 6
	s_waitcnt vmcnt(14)
	ds_write_b128 v2, v[10:13] offset:256
	v_add_u32_e32 v2, v2, v3
	v_add_u32_e32 v203, v192, v3
	v_add_u32_e32 v3, 0x6400, v2
	v_add_u32_e32 v2, 0x8600, v2
	s_add_u32 s18, s18, s59
	s_waitcnt vmcnt(13)
	ds_write2_b64 v3, v[14:15], v[16:17] offset1:1
	s_waitcnt vmcnt(12)
	ds_write2_b64 v2, v[18:19], v[20:21] offset1:1
	v_lshlrev_b32_e32 v2, 2, v187
	v_xor_b32_e32 v189, 0x80, v2
	v_lshlrev_b64 v[2:3], 14, v[24:25]
	s_addc_u32 s19, s19, 0
	v_lshl_add_u64 v[2:3], s[18:19], 0, v[2:3]
	v_lshl_add_u64 v[194:195], v[2:3], 0, v[0:1]
	v_lshlrev_b64 v[2:3], 7, v[24:25]
	v_lshl_add_u64 v[2:3], s[20:21], 0, v[2:3]
	s_add_u32 s18, s60, s22
	v_lshl_add_u64 v[196:197], v[2:3], 0, v[0:1]
	v_lshlrev_b64 v[2:3], 12, v[22:23]
	s_addc_u32 s19, 0, s23
	v_lshl_add_u64 v[2:3], s[18:19], 0, v[2:3]
	v_mov_b32_e32 v14, v1
	v_mov_b32_e32 v15, v1
	v_lshlrev_b32_e32 v186, 3, v30
	v_lshlrev_b32_e32 v204, 4, v31
	v_lshl_add_u64 v[198:199], v[2:3], 0, v[184:185]
	v_mov_b32_e32 v0, v1
	v_mov_b32_e32 v2, v1
	v_mov_b32_e32 v3, v1
	v_mov_b32_e32 v4, v1
	v_mov_b32_e32 v5, v1
	v_mov_b32_e32 v6, v1
	v_mov_b32_e32 v7, v1
	v_mov_b32_e32 v8, v1
	v_mov_b32_e32 v9, v1
	v_mov_b32_e32 v10, v1
	v_mov_b32_e32 v11, v1
	v_mov_b32_e32 v12, v1
	v_mov_b32_e32 v13, v1
	v_mov_b64_e32 v[30:31], v[14:15]
	v_mov_b64_e32 v[46:47], v[14:15]
	v_mov_b64_e32 v[62:63], v[14:15]
	v_mov_b64_e32 v[78:79], v[14:15]
	s_mov_b32 s57, 0
	v_mul_u32_u24_e32 v193, 0x190, v202
	v_mul_u32_u24_e32 v191, 0x88, v202
	v_mov_b32_e32 v185, 0
	v_mov_b64_e32 v[28:29], v[12:13]
	v_mov_b64_e32 v[26:27], v[10:11]
	v_mov_b64_e32 v[24:25], v[8:9]
	v_mov_b64_e32 v[22:23], v[6:7]
	v_mov_b64_e32 v[20:21], v[4:5]
	v_mov_b64_e32 v[18:19], v[2:3]
	v_mov_b64_e32 v[16:17], v[0:1]
	v_mov_b64_e32 v[44:45], v[12:13]
	v_mov_b64_e32 v[42:43], v[10:11]
	v_mov_b64_e32 v[40:41], v[8:9]
	v_mov_b64_e32 v[38:39], v[6:7]
	v_mov_b64_e32 v[36:37], v[4:5]
	v_mov_b64_e32 v[34:35], v[2:3]
	v_mov_b64_e32 v[32:33], v[0:1]
	v_mov_b64_e32 v[60:61], v[12:13]
	v_mov_b64_e32 v[58:59], v[10:11]
	v_mov_b64_e32 v[56:57], v[8:9]
	v_mov_b64_e32 v[54:55], v[6:7]
	v_mov_b64_e32 v[52:53], v[4:5]
	v_mov_b64_e32 v[50:51], v[2:3]
	v_mov_b64_e32 v[48:49], v[0:1]
	v_mov_b64_e32 v[76:77], v[12:13]
	v_mov_b64_e32 v[74:75], v[10:11]
	v_mov_b64_e32 v[72:73], v[8:9]
	v_mov_b64_e32 v[70:71], v[6:7]
	v_mov_b64_e32 v[68:69], v[4:5]
	v_mov_b64_e32 v[66:67], v[2:3]
	v_mov_b64_e32 v[64:65], v[0:1]
	s_waitcnt lgkmcnt(0)
	s_barrier
	v_mov_b32_e32 v216, 0
	v_mov_b32_e32 v217, 0
	v_mov_b32_e32 v218, 0
	v_mov_b32_e32 v219, 0
	v_mov_b32_e32 v220, 0
	v_mov_b32_e32 v221, 0
	v_mov_b32_e32 v222, 0
	v_mov_b32_e32 v223, 0
	v_mov_b32_e32 v224, 0
	v_mov_b32_e32 v225, 0
	v_mov_b32_e32 v226, 0
	v_mov_b32_e32 v227, 0
	v_mov_b32_e32 v228, 0
	v_mov_b32_e32 v229, 0
	v_mov_b32_e32 v230, 0
	v_mov_b32_e32 v231, 0
	s_add_u32 s70, s26, 0x11140000
	s_addc_u32 s71, s27, 0
	s_add_u32 s72, s26, 0x11160000
	s_addc_u32 s73, s27, 0
	s_add_u32 s74, s26, 0x13100000
	s_addc_u32 s75, s27, 0
	s_add_u32 s76, s26, 0x13200000
	s_addc_u32 s77, s27, 0
	s_mov_b64 s[78:79], s[26:27]
	v_add_u32_e32 v238, 0x6400, v203
	v_add_u32_e32 v239, 0x8600, v203
	v_add_u32_e32 v240, 0xa800, v238
	v_add_u32_e32 v241, 0xa800, v239

; DI void attn_unit(LAS unsigned char* lds, int wid, int b, int h, int qb) {
;     ...
;             float ls = 0.f;
; #pragma unroll
;             for (int i = 0; i < 16; ++i) { s0[i] = __builtin_amdgcn_exp2f(s0[i] - mnew); s1[i] = __builtin_amdgcn_exp2f(s1[i] - mnew); ls += s0[i] + s1[i]; }
.LBB0_1094:
	v_exp_f32_e32 v80, v80
	v_exp_f32_e32 v96, v96
	v_exp_f32_e32 v81, v81
	v_exp_f32_e32 v97, v97
	v_exp_f32_e32 v82, v82
	v_exp_f32_e32 v98, v98
	v_exp_f32_e32 v83, v83
	v_exp_f32_e32 v99, v99
	v_add_f32_e32 v208, v96, v80
	v_exp_f32_e32 v84, v84
	v_exp_f32_e32 v100, v100

; DI unsigned pk2(float a, float b) { f32x2 f = {a, b}; bf16v2 r = __builtin_convertvector(f, bf16v2); return __builtin_bit_cast(unsigned, r); }
; #define VLD(dst, j, dt) do { LAS unsigned char* va_ = vb + (32 * (dt) + n) * VROW + (16 * (j) + 4 * g) * 2; const u32x2 lo_ = *(const LAS u32x2*)(va_), hi_ = *(const LAS u32x2*)(va_ + 16); dst = (u32x4){lo_.x, lo_.y, hi_.x, hi_.y}; } while (0)
; DI void attn_unit(LAS unsigned char* lds, int wid, int b, int h, int qb) {
;     ...
;             for (int i = 0; i < 16; ++i) { s0[i] = __builtin_amdgcn_exp2f(s0[i] - mnew); s1[i] = __builtin_amdgcn_exp2f(s1[i] - mnew); ls += s0[i] + s1[i]; }
;             lrow = lrow * alpha + ls;
;             if (__builtin_amdgcn_ballot_w64(alpha != 1.f) != 0ull) {
; #pragma unroll
;                 for (int dt = 0; dt < 4; ++dt)
; #pragma unroll
;                     for (int i = 0; i < 16; ++i) o[dt][i] *= alpha;
;             }
;             bf16x8 pf[4];
; #pragma unroll
;             for (int jj = 0; jj < 2; ++jj) { u32x4 w0, w1;
;                 w0.x = pk2(s0[8 * jj + 0], s0[8 * jj + 1]); w0.y = pk2(s0[8 * jj + 2], s0[8 * jj + 3]); w0.z = pk2(s0[8 * jj + 4], s0[8 * jj + 5]); w0.w = pk2(s0[8 * jj + 6], s0[8 * jj + 7]);
;                 w1.x = pk2(s1[8 * jj + 0], s1[8 * jj + 1]); w1.y = pk2(s1[8 * jj + 2], s1[8 * jj + 3]); w1.z = pk2(s1[8 * jj + 4], s1[8 * jj + 5]); w1.w = pk2(s1[8 * jj + 6], s1[8 * jj + 7]);
;                 pf[jj] = __builtin_bit_cast(bf16x8, w0); pf[2 + jj] = __builtin_bit_cast(bf16x8, w1); }
; #pragma unroll
;             for (int j = 0; j < 4; ++j) {
;                 if (j < 3) {
; #pragma unroll
;                     for (int dt = 0; dt < 4; ++dt) VLD(vf[(j + 1) & 1][dt], j + 1, dt);
;                 }
; #pragma unroll
;                 for (int dt = 0; dt < 4; ++dt) o[dt] = __builtin_amdgcn_mfma_f32_32x32x16_bf16(__builtin_bit_cast(bf16x8, vf[j & 1][dt]), pf[j], o[dt], 0, 0, 0);
;                 __builtin_amdgcn_sched_barrier(0); }
	v_add_f32_e32 v209, v97, v81
	v_exp_f32_e32 v85, v85
	v_exp_f32_e32 v101, v101
	v_add_f32_e32 v208, v209, v208
	v_add_f32_e32 v209, v98, v82
	v_exp_f32_e32 v86, v86
	v_exp_f32_e32 v102, v102
	v_add_f32_e32 v208, v209, v208
	v_add_f32_e32 v209, v99, v83
	v_exp_f32_e32 v87, v87
	v_exp_f32_e32 v103, v103
	v_add_f32_e32 v208, v209, v208
	v_add_f32_e32 v209, v100, v84
	v_exp_f32_e32 v88, v88
	v_exp_f32_e32 v104, v104
	v_add_f32_e32 v208, v209, v208
	v_add_f32_e32 v209, v101, v85
	v_exp_f32_e32 v89, v89
	v_exp_f32_e32 v105, v105
	v_add_f32_e32 v208, v209, v208
	v_add_f32_e32 v209, v102, v86
	v_exp_f32_e32 v90, v90
	v_exp_f32_e32 v106, v106
	v_add_f32_e32 v208, v209, v208
	v_add_f32_e32 v209, v103, v87
	v_exp_f32_e32 v91, v91
	v_exp_f32_e32 v107, v107
	v_add_f32_e32 v208, v209, v208
	v_add_f32_e32 v209, v104, v88
	v_exp_f32_e32 v92, v92
	v_exp_f32_e32 v108, v108
	v_add_f32_e32 v208, v209, v208
	v_add_f32_e32 v209, v105, v89
	v_exp_f32_e32 v93, v93
	v_exp_f32_e32 v109, v109
	v_add_f32_e32 v208, v209, v208
	v_add_f32_e32 v209, v106, v90
	v_exp_f32_e32 v94, v94
	v_exp_f32_e32 v110, v110
	v_add_f32_e32 v208, v209, v208
	v_add_f32_e32 v209, v107, v91
	v_exp_f32_e32 v95, v95
	v_exp_f32_e32 v111, v111
	v_add_f32_e32 v208, v209, v208
	v_add_f32_e32 v209, v108, v92
	v_add_f32_e32 v208, v209, v208
	v_add_f32_e32 v209, v109, v93
	v_add_f32_e32 v208, v209, v208
	v_cvt_pk_bf16_f32 v80, v80, v81
	v_cvt_pk_bf16_f32 v81, v82, v83
	v_cvt_pk_bf16_f32 v82, v84, v85
	v_cvt_pk_bf16_f32 v83, v86, v87
	v_add_f32_e32 v84, v110, v94
	v_add_f32_e32 v84, v84, v208
	v_mfma_f32_32x32x16_bf16 v[64:79], v[168:171], v[80:83], v[64:79]
	v_add_f32_e32 v85, v111, v95
	v_add_f32_e32 v168, v85, v84
	v_cvt_pk_bf16_f32 v84, v96, v97
	v_cvt_pk_bf16_f32 v85, v98, v99
	v_cvt_pk_bf16_f32 v86, v100, v101
	v_cvt_pk_bf16_f32 v87, v102, v103
	v_cvt_pk_bf16_f32 v88, v88, v89
	v_mfma_f32_32x32x16_bf16 v[48:63], v[180:183], v[80:83], v[48:63]
	v_cvt_pk_bf16_f32 v89, v90, v91
	v_cvt_pk_bf16_f32 v90, v92, v93
	v_cvt_pk_bf16_f32 v91, v94, v95
	v_cvt_pk_bf16_f32 v92, v104, v105
	v_cvt_pk_bf16_f32 v93, v106, v107
	v_cvt_pk_bf16_f32 v94, v108, v109
	v_cvt_pk_bf16_f32 v95, v110, v111
	s_waitcnt lgkmcnt(1)
	v_mfma_f32_32x32x16_bf16 v[32:47], v[176:179], v[80:83], v[32:47]
	ds_read2_b64 v[96:99], v15 offset0:132 offset1:134
	ds_read2_b64 v[100:103], v205 offset0:164 offset1:166
	ds_read2_b64 v[104:107], v206 offset0:196 offset1:198
	ds_read2_b64 v[108:111], v207 offset0:228 offset1:230
	v_fmac_f32_e32 v168, v185, v0
	s_waitcnt lgkmcnt(4)
	v_mfma_f32_32x32x16_bf16 v[16:31], v[172:175], v[80:83], v[16:31]
	s_waitcnt lgkmcnt(3)
	v_mfma_f32_32x32x16_bf16 v[64:79], v[96:99], v[88:91], v[64:79]
	s_waitcnt lgkmcnt(2)
	v_mfma_f32_32x32x16_bf16 v[48:63], v[100:103], v[88:91], v[48:63]
	s_waitcnt lgkmcnt(1)
	v_mfma_f32_32x32x16_bf16 v[32:47], v[104:107], v[88:91], v[32:47]
	ds_read2_b64 v[80:83], v15 offset0:136 offset1:138
	ds_read2_b64 v[96:99], v205 offset0:168 offset1:170
	ds_read2_b64 v[100:103], v206 offset0:200 offset1:202
	ds_read2_b64 v[104:107], v207 offset0:232 offset1:234
	s_waitcnt lgkmcnt(4)
	v_mfma_f32_32x32x16_bf16 v[16:31], v[108:111], v[88:91], v[16:31]
	s_waitcnt lgkmcnt(3)
	v_mfma_f32_32x32x16_bf16 v[64:79], v[80:83], v[84:87], v[64:79]
	s_waitcnt lgkmcnt(2)
	v_mfma_f32_32x32x16_bf16 v[48:63], v[96:99], v[84:87], v[48:63]
	s_waitcnt lgkmcnt(1)
	v_mfma_f32_32x32x16_bf16 v[32:47], v[100:103], v[84:87], v[32:47]
	ds_read2_b64 v[80:83], v15 offset0:140 offset1:142
	ds_read2_b64 v[88:91], v205 offset0:172 offset1:174
	ds_read2_b64 v[96:99], v206 offset0:204 offset1:206
	ds_read2_b64 v[100:103], v207 offset0:236 offset1:238
	s_waitcnt lgkmcnt(4)
	v_mfma_f32_32x32x16_bf16 v[16:31], v[104:107], v[84:87], v[16:31]
	s_waitcnt lgkmcnt(3)
	v_mfma_f32_32x32x16_bf16 v[64:79], v[80:83], v[92:95], v[64:79]
	s_waitcnt lgkmcnt(2)
	v_mfma_f32_32x32x16_bf16 v[48:63], v[88:91], v[92:95], v[48:63]
	s_waitcnt lgkmcnt(1)
	v_mfma_f32_32x32x16_bf16 v[32:47], v[96:99], v[92:95], v[32:47]
	s_waitcnt lgkmcnt(0)
	v_mfma_f32_32x32x16_bf16 v[16:31], v[100:103], v[92:95], v[16:31]
	v_mov_b32_e32 v185, v168
	s_branch .LBB0_1096

; DI void attn_unit(LAS unsigned char* lds, int wid, int b, int h, int qb) {
;     ...
;         if (kt + 1 < nkt) A_WRITE(buf ^ 1);
;         __syncthreads();
.LBB0_1096:
	s_add_u32 s70, s70, 0x40000
	s_addc_u32 s71, s71, 0
	s_add_u32 s72, s72, 0x40000
	s_addc_u32 s73, s73, 0
	s_add_u32 s78, s78, 0x2000
	s_addc_u32 s79, s79, 0
	s_add_u32 s74, s74, 0x80
	s_addc_u32 s75, s75, 0
	s_add_u32 s76, s76, 0x80
	s_addc_u32 s77, s77, 0
	s_add_i32 s57, s57, 1
	s_cmp_lg_u32 s18, 0
	s_cbranch_scc1 .Lw2_b0
	s_waitcnt vmcnt(4)
	ds_write_b128 v190, v[2:5] offset:43008
	s_waitcnt vmcnt(3)
	ds_write_b128 v190, v[6:9] offset:55808
	s_waitcnt vmcnt(2)
	ds_write_b128 v192, v[10:13] offset:43264
	s_waitcnt vmcnt(1)
	ds_write2_b64 v240, v[160:161], v[162:163] offset1:1
	s_waitcnt vmcnt(0)
	ds_write2_b64 v241, v[164:165], v[166:167] offset1:1
	s_branch .Lw2_join
.Lw2_b0:
	s_waitcnt vmcnt(4)
	ds_write_b128 v190, v[2:5] offset:0
	s_waitcnt vmcnt(3)
	ds_write_b128 v190, v[6:9] offset:12800
	s_waitcnt vmcnt(2)
	ds_write_b128 v192, v[10:13] offset:256
	s_waitcnt vmcnt(1)
	ds_write2_b64 v238, v[160:161], v[162:163] offset1:1
	s_waitcnt vmcnt(0)
	ds_write2_b64 v239, v[164:165], v[166:167] offset1:1
.Lw2_join:
	s_cmp_eq_u32 s4, s57
	s_waitcnt lgkmcnt(0)
	s_barrier
	s_cbranch_scc1 .LBB0_1098
	v_mov_b32_e32 v172, v14
	s_branch .LBB0_1091
